# v30 + 64-byte alignment of hot loop headers
# baseline (speedup 1.0000x reference)
.LBB0_34:
	s_add_u32 s1, s30, 0x100
	s_addc_u32 s64, s31, 0
	s_ashr_i32 s25, s24, 31
	s_lshl_b64 s[26:27], s[24:25], 19
	s_add_u32 s28, s94, s26
	s_addc_u32 s29, s95, s27
	s_and_b64 s[26:27], s[8:9], exec
	s_cselect_b32 s25, s29, s3
	s_cselect_b32 s65, s28, s2
	s_ashr_i32 s23, s22, 31
	s_lshl_b64 s[26:27], s[22:23], 19
	s_add_u32 s26, s12, s26
	s_addc_u32 s27, s13, s27
	s_and_b64 s[34:35], s[8:9], exec
	s_cselect_b32 s23, s27, s31
	s_cselect_b32 s70, s26, s30
	s_add_u32 s30, s2, 0x40080
	s_addc_u32 s31, s3, 0
	v_lshl_add_u64 v[140:141], s[30:31], 0, v[136:137]
	v_lshl_add_u64 v[154:155], s[30:31], 0, v[138:139]
	s_mov_b32 s71, -2
	s_mov_b64 s[30:31], 0
	.p2align	6

.LBB0_87:
	v_mov_b32_e32 v22, v142
	s_lshl_b32 s5, s4, 2
	s_andn2_b32 s5, s5, 63
	v_ashrrev_i32_e32 v18, 3, v22
	v_add_u32_e32 v26, s5, v18
	v_lshlrev_b32_e32 v0, 3, v22
	v_ashrrev_i32_e32 v27, 31, v26
	v_and_b32_e32 v0, 56, v0
	s_waitcnt lgkmcnt(0)
	v_lshlrev_b64 v[2:3], 11, v[26:27]
	s_lshl_b32 s6, s4, 6
	v_lshl_add_u64 v[2:3], s[2:3], 0, v[2:3]
	v_lshlrev_b32_e32 v0, 1, v0
	s_and_b32 s14, s6, 0x3c0
	v_lshl_add_u64 v[6:7], v[2:3], 0, v[0:1]
	v_add_u32_e32 v2, s14, v18
	v_ashrrev_i32_e32 v3, 31, v2
	v_lshlrev_b64 v[2:3], 11, v[2:3]
	v_lshl_add_u64 v[2:3], s[12:13], 0, v[2:3]
	v_lshl_add_u64 v[14:15], v[2:3], 0, v[0:1]
	global_load_dwordx4 v[2:5], v[6:7], off
	s_nop 0
	global_load_dwordx4 v[6:9], v[6:7], off offset:128
	s_nop 0
	global_load_dwordx4 v[10:13], v[14:15], off
	s_nop 0
	global_load_dwordx4 v[14:17], v[14:15], off offset:128
	v_lshrrev_b32_e32 v19, 2, v22
	v_and_b32_e32 v32, 15, v22
	v_and_b32_e32 v33, 48, v19
	s_lshl_b32 s6, s0, 11
	v_or_b32_e32 v19, v33, v32
	v_and_b32_e32 v34, 0xffffffe0, v18
	s_and_b32 s48, s6, 0x1e0000
	s_and_b32 s6, s1, 0xffffffc0
	s_movk_i32 s15, 0x88
	v_mul_u32_u24_e32 v35, 0x88, v19
	v_or_b32_e32 v19, v34, v32
	s_ashr_i32 s7, s6, 31
	v_mul_lo_u32 v37, v19, s15
	v_ashrrev_i32_e32 v19, 31, v18
	v_bfe_u32 v27, v22, 4, 2
	v_mul_lo_u32 v23, v18, s15
	v_lshlrev_b64 v[20:21], 11, v[18:19]
	v_lshlrev_b32_e32 v22, 4, v22
	v_lshl_add_u64 v[18:19], v[18:19], 0, s[6:7]
	v_and_b32_e32 v22, 0x70, v22
	v_lshlrev_b64 v[18:19], 11, v[18:19]
	s_waitcnt lgkmcnt(0)
	s_barrier
	v_lshl_add_u64 v[20:21], s[48:49], 0, v[20:21]
	v_or_b32_e32 v18, v18, v22
	v_or_b32_e32 v20, v20, v22
	v_lshl_add_u64 v[30:31], s[50:51], 0, v[18:19]
	v_mov_b32_e32 v18, 0
	v_lshlrev_b32_e32 v36, 3, v27
	v_lshl_add_u64 v[28:29], s[16:17], 0, v[20:21]
	s_mov_b64 s[6:7], 0
	s_mov_b32 s15, 0
	v_lshlrev_b32_e32 v38, 1, v23
	v_mov_b32_e32 v19, v18
	v_mov_b32_e32 v20, v18
	v_mov_b32_e32 v21, v18
	v_mov_b32_e32 v22, v18
	v_mov_b32_e32 v23, v18
	v_mov_b32_e32 v24, v18
	v_mov_b32_e32 v25, v18
	.p2align	6

.LBB0_124:
	s_ashr_i32 s13, s12, 31
	v_mov_b64_e32 v[2:3], 0x5d8
	s_lshl_b64 s[14:15], s[12:13], 19
	v_cmp_lt_i64_e32 vcc, s[16:17], v[2:3]
	s_add_u32 s16, s94, s14
	s_addc_u32 s17, s95, s15
	s_and_b64 s[14:15], vcc, exec
	s_cselect_b32 s5, s17, s21
	s_cselect_b32 s13, s16, s20
	s_ashr_i32 s9, s8, 31
	s_lshl_b64 s[14:15], s[8:9], 19
	s_add_u32 s18, s27, s14
	s_addc_u32 s19, s28, s15
	s_and_b64 s[14:15], vcc, exec
	s_cselect_b32 s9, s19, s23
	s_cselect_b32 s14, s18, s22
	s_add_u32 s20, s20, 0x40080
	s_addc_u32 s21, s21, 0
	s_add_u32 s15, s22, 0x100
	v_mov_b32_e32 v2, 0
	s_addc_u32 s33, s23, 0
	s_mov_b32 s55, -2
	v_mov_b32_e32 v3, v2
	v_mov_b32_e32 v4, v2
	v_mov_b32_e32 v5, v2
	v_mov_b32_e32 v6, v2
	v_mov_b32_e32 v7, v2
	v_mov_b32_e32 v8, v2
	v_mov_b32_e32 v9, v2
	v_mov_b32_e32 v18, v2
	v_mov_b32_e32 v19, v2
	v_mov_b32_e32 v20, v2
	v_mov_b32_e32 v21, v2
	v_mov_b32_e32 v22, v2
	v_mov_b32_e32 v23, v2
	v_mov_b32_e32 v24, v2
	v_mov_b32_e32 v25, v2
	v_mov_b32_e32 v34, v2
	v_mov_b32_e32 v35, v2
	v_mov_b32_e32 v36, v2
	v_mov_b32_e32 v37, v2
	v_mov_b32_e32 v38, v2
	v_mov_b32_e32 v39, v2
	v_mov_b32_e32 v40, v2
	v_mov_b32_e32 v41, v2
	v_mov_b32_e32 v50, v2
	v_mov_b32_e32 v51, v2
	v_mov_b32_e32 v52, v2
	v_mov_b32_e32 v53, v2
	v_mov_b32_e32 v54, v2
	v_mov_b32_e32 v55, v2
	v_mov_b32_e32 v56, v2
	v_mov_b32_e32 v57, v2
	v_mov_b32_e32 v10, v2
	v_mov_b32_e32 v11, v2
	v_mov_b32_e32 v12, v2
	v_mov_b32_e32 v13, v2
	v_mov_b32_e32 v14, v2
	v_mov_b32_e32 v15, v2
	v_mov_b32_e32 v16, v2
	v_mov_b32_e32 v17, v2
	v_mov_b32_e32 v26, v2
	v_mov_b32_e32 v27, v2
	v_mov_b32_e32 v28, v2
	v_mov_b32_e32 v29, v2
	v_mov_b32_e32 v30, v2
	v_mov_b32_e32 v31, v2
	v_mov_b32_e32 v32, v2
	v_mov_b32_e32 v33, v2
	v_mov_b32_e32 v42, v2
	v_mov_b32_e32 v43, v2
	v_mov_b32_e32 v44, v2
	v_mov_b32_e32 v45, v2
	v_mov_b32_e32 v46, v2
	v_mov_b32_e32 v47, v2
	v_mov_b32_e32 v48, v2
	v_mov_b32_e32 v49, v2
	v_mov_b32_e32 v58, v2
	v_mov_b32_e32 v59, v2
	v_mov_b32_e32 v60, v2
	v_mov_b32_e32 v61, v2
	v_mov_b32_e32 v62, v2
	v_mov_b32_e32 v63, v2
	v_mov_b32_e32 v64, v2
	v_mov_b32_e32 v65, v2
	v_mov_b32_e32 v66, v2
	v_mov_b32_e32 v67, v2
	v_mov_b32_e32 v68, v2
	v_mov_b32_e32 v69, v2
	v_mov_b32_e32 v70, v2
	v_mov_b32_e32 v71, v2
	v_mov_b32_e32 v72, v2
	v_mov_b32_e32 v73, v2
	v_mov_b32_e32 v82, v2
	v_mov_b32_e32 v83, v2
	v_mov_b32_e32 v84, v2
	v_mov_b32_e32 v85, v2
	v_mov_b32_e32 v86, v2
	v_mov_b32_e32 v87, v2
	v_mov_b32_e32 v88, v2
	v_mov_b32_e32 v89, v2
	v_mov_b32_e32 v98, v2
	v_mov_b32_e32 v99, v2
	v_mov_b32_e32 v100, v2
	v_mov_b32_e32 v101, v2
	v_mov_b32_e32 v102, v2
	v_mov_b32_e32 v103, v2
	v_mov_b32_e32 v104, v2
	v_mov_b32_e32 v105, v2
	v_mov_b32_e32 v114, v2
	v_mov_b32_e32 v115, v2
	v_mov_b32_e32 v116, v2
	v_mov_b32_e32 v117, v2
	v_mov_b32_e32 v118, v2
	v_mov_b32_e32 v119, v2
	v_mov_b32_e32 v120, v2
	v_mov_b32_e32 v121, v2
	v_mov_b32_e32 v74, v2
	v_mov_b32_e32 v75, v2
	v_mov_b32_e32 v76, v2
	v_mov_b32_e32 v77, v2
	v_mov_b32_e32 v78, v2
	v_mov_b32_e32 v79, v2
	v_mov_b32_e32 v80, v2
	v_mov_b32_e32 v81, v2
	v_mov_b32_e32 v90, v2
	v_mov_b32_e32 v91, v2
	v_mov_b32_e32 v92, v2
	v_mov_b32_e32 v93, v2
	v_mov_b32_e32 v94, v2
	v_mov_b32_e32 v95, v2
	v_mov_b32_e32 v96, v2
	v_mov_b32_e32 v97, v2
	v_mov_b32_e32 v106, v2
	v_mov_b32_e32 v107, v2
	v_mov_b32_e32 v108, v2
	v_mov_b32_e32 v109, v2
	v_mov_b32_e32 v110, v2
	v_mov_b32_e32 v111, v2
	v_mov_b32_e32 v112, v2
	v_mov_b32_e32 v113, v2
	v_mov_b32_e32 v122, v2
	v_mov_b32_e32 v123, v2
	v_mov_b32_e32 v124, v2
	v_mov_b32_e32 v125, v2
	v_mov_b32_e32 v126, v2
	v_mov_b32_e32 v127, v2
	v_mov_b32_e32 v128, v2
	v_mov_b32_e32 v129, v2
	.p2align	6

.LBB0_171:
	s_add_i32 vcc_lo, s1, s30
	s_mov_b64 s[42:43], s[6:7]
	s_mov_b64 s[44:45], s[2:3]
	v_mov_b64_e32 v[2:3], v[158:159]
	v_mov_b64_e32 v[160:161], v[156:157]
	.p2align	6

.LBB0_227:
	v_mov_b32_e32 v35, v142
	s_lshl_b32 s1, s15, 2
	s_andn2_b32 s1, s1, 63
	v_ashrrev_i32_e32 v34, 3, v35
	v_lshlrev_b32_e32 v0, 3, v35
	v_and_b32_e32 v6, 56, v0
	v_add_u32_e32 v0, s1, v34
	s_waitcnt lgkmcnt(0)
	v_mad_u64_u32 v[2:3], s[8:9], v0, s18, 0
	s_waitcnt lgkmcnt(0)
	v_ashrrev_i32_e32 v4, 31, v0
	v_mov_b32_e32 v0, v3
	v_mad_u64_u32 v[4:5], s[8:9], v4, s18, v[0:1]
	s_lshl_b32 s0, s15, 6
	v_mov_b32_e32 v3, v4
	s_and_b32 s0, s0, 0x3c0
	v_lshl_add_u64 v[2:3], v[2:3], 1, s[2:3]
	v_lshlrev_b32_e32 v28, 1, v6
	v_mov_b32_e32 v29, v1
	v_add_u32_e32 v0, s0, v34
	v_lshl_add_u64 v[18:19], v[2:3], 0, v[28:29]
	v_mad_u64_u32 v[2:3], s[8:9], v0, s18, 0
	v_ashrrev_i32_e32 v4, 31, v0
	v_mov_b32_e32 v0, v3
	v_mad_u64_u32 v[4:5], s[8:9], v4, s18, v[0:1]
	v_mov_b32_e32 v3, v4
	v_lshl_add_u64 v[2:3], v[2:3], 1, s[16:17]
	v_lshl_add_u64 v[20:21], v[2:3], 0, v[28:29]
	global_load_dwordx4 v[2:5], v[18:19], off
	global_load_dwordx4 v[6:9], v[18:19], off offset:128
	global_load_dwordx4 v[10:13], v[20:21], off
	global_load_dwordx4 v[14:17], v[20:21], off offset:128
	s_movk_i32 s8, 0x88
	v_mul_lo_u32 v0, v34, s8
	v_lshlrev_b32_e32 v42, 1, v0
	v_add3_u32 v0, s89, v42, v28
	s_waitcnt lgkmcnt(0)
	s_barrier
	v_bfe_u32 v29, v35, 4, 2
	v_lshl_add_u32 v22, v29, 4, s89
	v_and_b32_e32 v26, 0xffffffe0, v34
	s_addk_i32 s1, 0x4000
	s_and_b32 s48, s5, 0x3c0
	s_and_b32 s28, s14, 0xffffffc0
	s_ashr_i32 s29, s28, 31
	v_lshlrev_b32_e32 v45, 3, v29
	s_waitcnt vmcnt(3)
	ds_write_b128 v0, v[2:5]
	s_waitcnt vmcnt(2)
	ds_write_b128 v0, v[6:9] offset:128
	s_waitcnt vmcnt(1)
	ds_write_b128 v0, v[10:13] offset:34816
	s_waitcnt vmcnt(0)
	ds_write_b128 v0, v[14:17] offset:34944
	s_waitcnt lgkmcnt(0)
	s_barrier
	global_load_dwordx4 v[6:9], v[18:19], off offset:256
	global_load_dwordx4 v[10:13], v[18:19], off offset:384
	global_load_dwordx4 v[14:17], v[20:21], off offset:256
	s_nop 0
	global_load_dwordx4 v[18:21], v[20:21], off offset:384
	v_lshrrev_b32_e32 v2, 2, v35
	v_and_b32_e32 v0, 15, v35
	v_and_b32_e32 v37, 48, v2
	v_or_b32_e32 v2, v37, v0
	v_mul_u32_u24_e32 v43, 0x88, v2
	v_lshl_add_u32 v27, v43, 1, v22
	ds_read_b128 v[2:5], v27 offset:34816
	v_or_b32_e32 v23, v26, v0
	v_mul_lo_u32 v44, v23, s8
	v_lshl_add_u32 v36, v44, 1, v22
	ds_read_b128 v[22:25], v36
	ds_read_b128 v[30:33], v36 offset:4352
	ds_read_b128 v[38:41], v27 offset:34880
	s_waitcnt lgkmcnt(2)
	v_mfma_f32_16x16x32_bf16 v[22:25], v[2:5], v[22:25], 0
	v_or_b32_e32 v0, s1, v0
	v_add_u32_e32 v26, v0, v26
	v_and_b32_e32 v0, 7, v35
	s_waitcnt lgkmcnt(1)
	v_mfma_f32_16x16x32_bf16 v[2:5], v[2:5], v[30:33], 0
	ds_read_b128 v[30:33], v36 offset:64
	v_ashrrev_i32_e32 v35, 31, v34
	s_mov_b32 s8, 1
	s_waitcnt lgkmcnt(0)
	v_mfma_f32_16x16x32_bf16 v[22:25], v[38:41], v[30:33], v[22:25]
	ds_read_b128 v[30:33], v36 offset:4416
	ds_read_b128 v[46:49], v27 offset:34944
	ds_read_b128 v[50:53], v36 offset:128
	v_lshlrev_b32_e32 v0, 4, v0
	s_waitcnt lgkmcnt(2)
	v_mfma_f32_16x16x32_bf16 v[2:5], v[38:41], v[30:33], v[2:5]
	ds_read_b128 v[30:33], v36 offset:4480
	ds_read_b128 v[38:41], v27 offset:35008
	v_ashrrev_i32_e32 v27, 31, v26
	s_mov_b32 s1, 64
	s_waitcnt lgkmcnt(2)
	v_mfma_f32_16x16x32_bf16 v[22:25], v[46:49], v[50:53], v[22:25]
	ds_read_b128 v[50:53], v36 offset:192
	s_waitcnt lgkmcnt(2)
	v_mfma_f32_16x16x32_bf16 v[2:5], v[46:49], v[30:33], v[2:5]
	ds_read_b128 v[30:33], v36 offset:4544
	v_mov_b64_e32 v[46:47], s[16:17]
	s_waitcnt lgkmcnt(0)
	v_mfma_f32_16x16x32_bf16 v[2:5], v[38:41], v[30:33], v[2:5]
	v_lshl_add_u64 v[32:33], s[48:49], 0, v[34:35]
	v_mul_lo_u32 v36, s12, v33
	v_lshl_add_u64 v[34:35], v[34:35], 0, s[28:29]
	v_mfma_f32_16x16x32_bf16 v[22:25], v[38:41], v[50:53], v[22:25]
	v_mul_lo_u32 v38, s13, v32
	v_mad_u64_u32 v[32:33], s[30:31], s12, v32, v[46:47]
	v_add3_u32 v33, v38, v33, v36
	v_mov_b64_e32 v[38:39], 0x8000
	v_lshl_add_u64 v[38:39], v[34:35], 1, v[38:39]
	v_mov_b64_e32 v[34:35], s[20:21]
	v_mad_u64_u32 v[34:35], s[28:29], s18, v38, v[34:35]
	v_mov_b32_e32 v36, v35
	v_mad_u64_u32 v[38:39], s[28:29], s18, v39, v[36:37]
	v_lshl_add_u64 v[30:31], v[26:27], 3, s[24:25]
	v_mov_b32_e32 v35, v38
	.p2align	6

.LBB0_259:
	s_or_b64 exec, exec, s[84:85]
	v_mov_b32_e32 v38, s92
	ds_read_b32 v38, v38
	s_mov_b64 s[84:85], 0x2000
	s_add_u32 s56, s56, 0x20000
	v_lshl_add_u64 v[68:69], v[68:69], 0, s[84:85]
	s_mov_b64 s[84:85], 0xa8000
	s_waitcnt lgkmcnt(0)
	v_mul_f32_e32 v38, 0x3fb8aa3b, v38
	v_exp_f32_e32 v154, v38
	ds_read_b128 v[38:41], v92 offset:62464
	ds_read_b128 v[42:45], v93 offset:62464
	ds_read_b128 v[84:87], v118 offset:34816
	s_addc_u32 s57, s57, 0
	s_waitcnt vmcnt(11)
	v_pk_mul_f32 v[4:5], v[4:5], v[154:155] op_sel_hi:[1,0]
	v_pk_mul_f32 v[2:3], v[2:3], v[154:155] op_sel_hi:[1,0]
	v_pk_mul_f32 v[36:37], v[36:37], v[154:155] op_sel_hi:[1,0]
	v_pk_mul_f32 v[34:35], v[34:35], v[154:155] op_sel_hi:[1,0]
	s_waitcnt lgkmcnt(0)
	v_mfma_f32_16x16x32_bf16 v[2:5], v[38:41], v[84:87], v[2:5]
	ds_read_b128 v[84:87], v119 offset:34816
	v_pk_mul_f32 v[32:33], v[32:33], v[154:155] op_sel_hi:[1,0]
	v_pk_mul_f32 v[30:31], v[30:31], v[154:155] op_sel_hi:[1,0]
	s_waitcnt lgkmcnt(0)
	v_mfma_f32_16x16x32_bf16 v[2:5], v[42:45], v[84:87], v[2:5]
	ds_read_b128 v[84:87], v120 offset:34816
	v_pk_mul_f32 v[28:29], v[28:29], v[154:155] op_sel_hi:[1,0]
	v_pk_mul_f32 v[26:27], v[26:27], v[154:155] op_sel_hi:[1,0]
	s_waitcnt lgkmcnt(0)
	v_mfma_f32_16x16x32_bf16 v[34:37], v[38:41], v[84:87], v[34:37]
	ds_read_b128 v[84:87], v121 offset:34816
	v_lshl_add_u64 v[70:71], v[70:71], 0, s[84:85]
	s_mov_b64 s[0:1], 0x40000
	s_waitcnt lgkmcnt(0)
	v_mfma_f32_16x16x32_bf16 v[34:37], v[42:45], v[84:87], v[34:37]
	ds_read_b128 v[84:87], v122 offset:34816
	s_mov_b64 s[84:85], 0x200
	v_lshl_add_u64 v[72:73], v[72:73], 0, s[0:1]
	s_waitcnt lgkmcnt(0)
	v_mfma_f32_16x16x32_bf16 v[30:33], v[38:41], v[84:87], v[30:33]
	ds_read_b128 v[84:87], v123 offset:34816
	v_lshl_add_u64 v[74:75], v[74:75], 0, s[86:87]
	v_lshl_add_u64 v[76:77], v[76:77], 0, s[86:87]
	s_waitcnt lgkmcnt(0)
	v_mfma_f32_16x16x32_bf16 v[30:33], v[42:45], v[84:87], v[30:33]
	ds_read_b128 v[84:87], v124 offset:34816
	v_lshl_add_u64 v[78:79], v[78:79], 0, s[86:87]
	v_lshl_add_u64 v[80:81], v[80:81], 0, s[84:85]
	s_waitcnt lgkmcnt(0)
	v_mfma_f32_16x16x32_bf16 v[26:29], v[38:41], v[84:87], v[26:29]
	ds_read_b128 v[38:41], v125 offset:34816
	s_waitcnt lgkmcnt(0)
	s_barrier
	s_waitcnt lgkmcnt(0)
	v_mfma_f32_16x16x32_bf16 v[26:29], v[42:45], v[38:41], v[26:29]
	s_cmp_eq_u32 s56, 0x400000
	v_mov_b32_e32 v163, v162
	v_mov_b32_e32 v164, v158
	v_mov_b32_e32 v86, v156
	v_mov_b32_e32 v84, v0
	s_waitcnt vmcnt(8)
	v_mov_b32_e32 v160, v161
	v_mov_b32_e32 v154, v159
	v_mov_b32_e32 v153, v157
	v_mov_b32_e32 v141, v155
	s_cbranch_scc1 .LBB0_281
	.p2align	6

.LBB0_299:
	s_mov_b32 s18, 0
	v_mov_b32_e32 v37, v62
	v_mov_b32_e32 v68, v56
	s_mov_b32 s19, s23
	.p2align	6

.LBB0_315:
	s_ashr_i32 s19, s18, 31
	s_lshl_b64 s[4:5], s[18:19], 18
	v_readlane_b32 s0, v255, 17
	v_readlane_b32 s1, v255, 18
	s_add_u32 s26, s0, s4
	v_cmp_lt_i64_e32 vcc, s[8:9], v[150:151]
	s_addc_u32 s27, s1, s5
	s_and_b64 s[4:5], vcc, exec
	s_cselect_b32 s3, s27, s37
	s_cselect_b32 s4, s26, s36
	s_ashr_i32 s17, s16, 31
	s_lshl_b64 s[8:9], s[16:17], 18
	s_add_u32 s28, s40, s8
	s_addc_u32 s29, s41, s9
	s_and_b64 s[8:9], vcc, exec
	s_cselect_b32 s5, s29, s35
	s_cselect_b32 s17, s28, s34
	s_add_u32 s8, s36, 0x20080
	s_addc_u32 s9, s37, 0
	s_add_u32 s19, s34, 0x100
	v_mov_b32_e32 v2, 0
	s_addc_u32 s31, s35, 0
	s_mov_b32 s33, -2
	v_mov_b32_e32 v3, v2
	v_mov_b32_e32 v4, v2
	v_mov_b32_e32 v5, v2
	v_mov_b32_e32 v66, v2
	v_mov_b32_e32 v67, v2
	v_mov_b32_e32 v68, v2
	v_mov_b32_e32 v69, v2
	v_mov_b32_e32 v10, v2
	v_mov_b32_e32 v11, v2
	v_mov_b32_e32 v12, v2
	v_mov_b32_e32 v13, v2
	v_mov_b32_e32 v74, v2
	v_mov_b32_e32 v75, v2
	v_mov_b32_e32 v76, v2
	v_mov_b32_e32 v77, v2
	v_mov_b32_e32 v18, v2
	v_mov_b32_e32 v19, v2
	v_mov_b32_e32 v20, v2
	v_mov_b32_e32 v21, v2
	v_mov_b32_e32 v82, v2
	v_mov_b32_e32 v83, v2
	v_mov_b32_e32 v84, v2
	v_mov_b32_e32 v85, v2
	v_mov_b32_e32 v26, v2
	v_mov_b32_e32 v27, v2
	v_mov_b32_e32 v28, v2
	v_mov_b32_e32 v29, v2
	v_mov_b32_e32 v90, v2
	v_mov_b32_e32 v91, v2
	v_mov_b32_e32 v92, v2
	v_mov_b32_e32 v93, v2
	v_mov_b32_e32 v6, v2
	v_mov_b32_e32 v7, v2
	v_mov_b32_e32 v8, v2
	v_mov_b32_e32 v9, v2
	v_mov_b32_e32 v70, v2
	v_mov_b32_e32 v71, v2
	v_mov_b32_e32 v72, v2
	v_mov_b32_e32 v73, v2
	v_mov_b32_e32 v14, v2
	v_mov_b32_e32 v15, v2
	v_mov_b32_e32 v16, v2
	v_mov_b32_e32 v17, v2
	v_mov_b32_e32 v78, v2
	v_mov_b32_e32 v79, v2
	v_mov_b32_e32 v80, v2
	v_mov_b32_e32 v81, v2
	v_mov_b32_e32 v22, v2
	v_mov_b32_e32 v23, v2
	v_mov_b32_e32 v24, v2
	v_mov_b32_e32 v25, v2
	v_mov_b32_e32 v86, v2
	v_mov_b32_e32 v87, v2
	v_mov_b32_e32 v88, v2
	v_mov_b32_e32 v89, v2
	v_mov_b32_e32 v30, v2
	v_mov_b32_e32 v31, v2
	v_mov_b32_e32 v32, v2
	v_mov_b32_e32 v33, v2
	v_mov_b32_e32 v102, v2
	v_mov_b32_e32 v103, v2
	v_mov_b32_e32 v104, v2
	v_mov_b32_e32 v105, v2
	v_mov_b32_e32 v34, v2
	v_mov_b32_e32 v35, v2
	v_mov_b32_e32 v36, v2
	v_mov_b32_e32 v37, v2
	v_mov_b32_e32 v106, v2
	v_mov_b32_e32 v107, v2
	v_mov_b32_e32 v108, v2
	v_mov_b32_e32 v109, v2
	v_mov_b32_e32 v42, v2
	v_mov_b32_e32 v43, v2
	v_mov_b32_e32 v44, v2
	v_mov_b32_e32 v45, v2
	v_mov_b32_e32 v114, v2
	v_mov_b32_e32 v115, v2
	v_mov_b32_e32 v116, v2
	v_mov_b32_e32 v117, v2
	v_mov_b32_e32 v50, v2
	v_mov_b32_e32 v51, v2
	v_mov_b32_e32 v52, v2
	v_mov_b32_e32 v53, v2
	v_mov_b32_e32 v122, v2
	v_mov_b32_e32 v123, v2
	v_mov_b32_e32 v124, v2
	v_mov_b32_e32 v125, v2
	v_mov_b32_e32 v58, v2
	v_mov_b32_e32 v59, v2
	v_mov_b32_e32 v60, v2
	v_mov_b32_e32 v61, v2
	v_mov_b32_e32 v130, v2
	v_mov_b32_e32 v131, v2
	v_mov_b32_e32 v132, v2
	v_mov_b32_e32 v133, v2
	v_mov_b32_e32 v38, v2
	v_mov_b32_e32 v39, v2
	v_mov_b32_e32 v40, v2
	v_mov_b32_e32 v41, v2
	v_mov_b32_e32 v110, v2
	v_mov_b32_e32 v111, v2
	v_mov_b32_e32 v112, v2
	v_mov_b32_e32 v113, v2
	v_mov_b32_e32 v46, v2
	v_mov_b32_e32 v47, v2
	v_mov_b32_e32 v48, v2
	v_mov_b32_e32 v49, v2
	v_mov_b32_e32 v118, v2
	v_mov_b32_e32 v119, v2
	v_mov_b32_e32 v120, v2
	v_mov_b32_e32 v121, v2
	v_mov_b32_e32 v54, v2
	v_mov_b32_e32 v55, v2
	v_mov_b32_e32 v56, v2
	v_mov_b32_e32 v57, v2
	v_mov_b32_e32 v126, v2
	v_mov_b32_e32 v127, v2
	v_mov_b32_e32 v128, v2
	v_mov_b32_e32 v129, v2
	v_mov_b32_e32 v62, v2
	v_mov_b32_e32 v63, v2
	v_mov_b32_e32 v64, v2
	v_mov_b32_e32 v65, v2
	v_mov_b32_e32 v134, v2
	v_mov_b32_e32 v135, v2
	v_mov_b32_e32 v136, v2
	v_mov_b32_e32 v137, v2
	.p2align	6

.LBB0_679:
	v_mul_f32_e32 v0, 0x3fb8aa3b, v0
	v_exp_f32_e32 v14, v0
	v_mul_f32_e32 v0, 0x3fb8aa3b, v2
	v_exp_f32_e32 v12, v0
	v_mul_f32_e32 v0, 0x3fb8aa3b, v4
	v_exp_f32_e32 v10, v0
	v_mul_f32_e32 v0, 0x3fb8aa3b, v6
	v_exp_f32_e32 v8, v0
	v_mul_f32_e32 v0, 0x3fb8aa3b, v16
	v_exp_f32_e32 v6, v0
	v_mul_f32_e32 v0, 0x3fb8aa3b, v78
	v_exp_f32_e32 v4, v0
	v_mul_f32_e32 v0, 0x3fb8aa3b, v79
	v_lshl_add_u64 v[78:79], s[50:51], 0, v[140:141]
	s_mov_b64 s[6:7], 0x14711c00
	v_exp_f32_e32 v2, v0
	v_mul_f32_e32 v0, 0x3fb8aa3b, v80
	v_lshl_add_u64 v[80:81], v[78:79], 0, s[6:7]
	s_mov_b32 s6, 0x14711000
	v_add_co_u32_e32 v78, vcc, s6, v78
	v_pk_mul_f32 v[48:49], v[14:15], v[48:49] op_sel_hi:[0,1]
	s_nop 0
	v_addc_co_u32_e32 v79, vcc, 0, v79, vcc
	global_load_dwordx4 v[82:85], v[78:79], off offset:3072
	s_nop 0
	global_load_dwordx4 v[78:81], v[80:81], off offset:16
	s_waitcnt lgkmcnt(0)
	s_barrier
	ds_read_b128 v[86:89], v160
	ds_read_b128 v[90:93], v124
	ds_read_b128 v[94:97], v125
	ds_read_b128 v[218:221], v126
	ds_read_b128 v[98:101], v193
	s_waitcnt lgkmcnt(3)
	v_mfma_f32_16x16x32_bf16 v[90:93], v[86:89], v[90:93], 0
	v_mul_f32_e64 v46, v14, v46
	v_mul_f32_e64 v47, v14, v47
	v_pk_mul_f32 v[76:77], v[12:13], v[76:77] op_sel_hi:[0,1]
	v_pk_mul_f32 v[74:75], v[12:13], v[74:75] op_sel_hi:[0,1]
	s_waitcnt lgkmcnt(2)
	v_mfma_f32_16x16x32_bf16 v[94:97], v[86:89], v[94:97], 0
	v_mul_f32_e64 v68, v10, v68
	v_mul_f32_e64 v69, v10, v69
	v_pk_mul_f32 v[66:67], v[10:11], v[66:67] op_sel_hi:[0,1]
	v_pk_mul_f32 v[60:61], v[8:9], v[60:61] op_sel_hi:[0,1]
	s_waitcnt lgkmcnt(0)
	v_mfma_f32_16x16x32_bf16 v[98:101], v[86:89], v[98:101], 0
	v_mul_f32_e64 v58, v8, v58
	v_mul_f32_e64 v59, v8, v59
	v_pk_mul_f32 v[56:57], v[6:7], v[56:57] op_sel_hi:[0,1]
	v_pk_mul_f32 v[54:55], v[6:7], v[54:55] op_sel_hi:[0,1]
	v_mfma_f32_16x16x32_bf16 v[86:89], v[86:89], v[218:221], 0
	ds_read_b128 v[218:221], v160 offset:64
	ds_read_b128 v[222:225], v124 offset:64
	v_pk_mul_f32 v[52:53], v[4:5], v[52:53] op_sel_hi:[0,1]
	v_pk_mul_f32 v[50:51], v[4:5], v[50:51] op_sel_hi:[0,1]
	s_waitcnt lgkmcnt(0)
	v_mfma_f32_16x16x32_bf16 v[90:93], v[218:221], v[222:225], v[90:93]
	ds_read_b128 v[222:225], v125 offset:64
	v_pk_mul_f32 v[72:73], v[2:3], v[72:73] op_sel_hi:[0,1]
	v_pk_mul_f32 v[70:71], v[2:3], v[70:71] op_sel_hi:[0,1]
	s_waitcnt lgkmcnt(0)
	v_mfma_f32_16x16x32_bf16 v[94:97], v[218:221], v[222:225], v[94:97]
	ds_read_b128 v[222:225], v193 offset:64
	v_exp_f32_e32 v0, v0
	v_add_u32_e32 v2, 0x8c00, v202
	s_waitcnt lgkmcnt(0)
	v_mfma_f32_16x16x32_bf16 v[98:101], v[218:221], v[222:225], v[98:101]
	ds_read_b128 v[222:225], v126 offset:64
	v_pk_mul_f32 v[64:65], v[0:1], v[64:65] op_sel_hi:[0,1]
	v_pk_mul_f32 v[62:63], v[0:1], v[62:63] op_sel_hi:[0,1]
	s_waitcnt lgkmcnt(0)
	v_mfma_f32_16x16x32_bf16 v[86:89], v[218:221], v[222:225], v[86:89]
	ds_read_b128 v[218:221], v160 offset:128
	ds_read_b128 v[222:225], v124 offset:128
	v_add_u32_e32 v0, 0x8800, v202
	v_and_b32_e32 v4, 64, v177
	s_waitcnt lgkmcnt(0)
	v_mfma_f32_16x16x32_bf16 v[90:93], v[218:221], v[222:225], v[90:93]
	ds_read_b128 v[222:225], v125 offset:128
	v_add_u32_e32 v4, 64, v4
	s_mov_b32 s0, 0x25f91000
	s_waitcnt lgkmcnt(0)
	v_mfma_f32_16x16x32_bf16 v[94:97], v[218:221], v[222:225], v[94:97]
	ds_read_b128 v[222:225], v193 offset:128
	s_add_i32 s5, s5, -1
	s_mov_b64 s[6:7], 0x20000
	s_waitcnt lgkmcnt(0)
	v_mfma_f32_16x16x32_bf16 v[98:101], v[218:221], v[222:225], v[98:101]
	ds_read_b128 v[222:225], v126 offset:128
	v_lshl_add_u64 v[132:133], v[132:133], 0, s[8:9]
	v_lshl_add_u64 v[134:135], v[134:135], 0, s[8:9]
	s_waitcnt lgkmcnt(0)
	v_mfma_f32_16x16x32_bf16 v[86:89], v[218:221], v[222:225], v[86:89]
	ds_read_b128 v[218:221], v160 offset:192
	ds_read_b128 v[222:225], v124 offset:192
	v_lshl_add_u64 v[136:137], v[136:137], 0, s[8:9]
	v_lshl_add_u64 v[140:141], v[140:141], 0, s[86:87]
	s_waitcnt lgkmcnt(0)
	v_mfma_f32_16x16x32_bf16 v[90:93], v[218:221], v[222:225], v[90:93]
	ds_read_b128 v[222:225], v125 offset:192
	s_cmp_lg_u32 s5, 0
	s_waitcnt lgkmcnt(0)
	v_mfma_f32_16x16x32_bf16 v[94:97], v[218:221], v[222:225], v[94:97]
	ds_read_b128 v[222:225], v193 offset:192
	s_waitcnt lgkmcnt(0)
	v_mfma_f32_16x16x32_bf16 v[98:101], v[218:221], v[222:225], v[98:101]
	ds_read_b128 v[222:225], v126 offset:192
	s_waitcnt lgkmcnt(0)
	v_mfma_f32_16x16x32_bf16 v[86:89], v[218:221], v[222:225], v[86:89]
	ds_read_b128 v[218:221], v161
	ds_read_b128 v[222:225], v128 offset:53248
	s_waitcnt lgkmcnt(0)
	v_mfma_f32_16x16x32_bf16 v[90:93], v[218:221], v[222:225], v[90:93]
	ds_read_b128 v[222:225], v127 offset:53248
	s_waitcnt lgkmcnt(0)
	v_mfma_f32_16x16x32_bf16 v[94:97], v[218:221], v[222:225], v[94:97]
	ds_read_b128 v[222:225], v129 offset:53248
	s_waitcnt lgkmcnt(0)
	v_mfma_f32_16x16x32_bf16 v[98:101], v[218:221], v[222:225], v[98:101]
	ds_read_b128 v[222:225], v130 offset:53248
	s_waitcnt lgkmcnt(0)
	v_mfma_f32_16x16x32_bf16 v[218:221], v[218:221], v[222:225], v[86:89]
	ds_read_b128 v[222:225], v161 offset:64
	s_nop 1
	ds_read_b128 v[86:89], v128 offset:53312
	s_waitcnt lgkmcnt(0)
	v_mfma_f32_16x16x32_bf16 v[86:89], v[222:225], v[86:89], v[90:93]
	s_nop 2
	ds_read_b128 v[90:93], v127 offset:53312
	s_waitcnt lgkmcnt(0)
	v_mfma_f32_16x16x32_bf16 v[90:93], v[222:225], v[90:93], v[94:97]
	s_nop 2
	ds_read_b128 v[94:97], v129 offset:53312
	s_waitcnt lgkmcnt(0)
	v_mfma_f32_16x16x32_bf16 v[94:97], v[222:225], v[94:97], v[98:101]
	s_nop 2
	ds_read_b128 v[98:101], v130 offset:53312
	s_waitcnt lgkmcnt(0)
	v_mfma_f32_16x16x32_bf16 v[98:101], v[222:225], v[98:101], v[218:221]
	s_nop 2
	ds_read_b128 v[218:221], v120 offset:53248
	ds_read_b128 v[222:225], v120 offset:53312
	ds_read_b128 v[226:229], v131 offset:34816
	s_waitcnt lgkmcnt(0)
	v_mfma_f32_16x16x32_bf16 v[46:49], v[218:221], v[226:229], v[46:49]
	ds_read_b128 v[226:229], v131 offset:34880
	s_waitcnt lgkmcnt(0)
	v_mfma_f32_16x16x32_bf16 v[46:49], v[222:225], v[226:229], v[46:49]
	ds_read_b128 v[226:229], v195 offset:34816
	s_waitcnt lgkmcnt(0)
	v_mfma_f32_16x16x32_bf16 v[74:77], v[218:221], v[226:229], v[74:77]
	ds_read_b128 v[226:229], v195 offset:34880
	s_waitcnt lgkmcnt(0)
	v_mfma_f32_16x16x32_bf16 v[74:77], v[222:225], v[226:229], v[74:77]
	ds_read_b128 v[226:229], v196 offset:34816
	s_waitcnt lgkmcnt(0)
	v_mfma_f32_16x16x32_bf16 v[66:69], v[218:221], v[226:229], v[66:69]
	ds_read_b128 v[226:229], v196 offset:34880
	s_waitcnt lgkmcnt(0)
	v_mfma_f32_16x16x32_bf16 v[66:69], v[222:225], v[226:229], v[66:69]
	ds_read_b128 v[226:229], v197 offset:34816
	s_waitcnt lgkmcnt(0)
	v_mfma_f32_16x16x32_bf16 v[58:61], v[218:221], v[226:229], v[58:61]
	ds_read_b128 v[226:229], v197 offset:34880
	s_waitcnt lgkmcnt(0)
	v_mfma_f32_16x16x32_bf16 v[58:61], v[222:225], v[226:229], v[58:61]
	ds_read_b128 v[226:229], v198 offset:34816
	s_waitcnt lgkmcnt(0)
	v_mfma_f32_16x16x32_bf16 v[54:57], v[218:221], v[226:229], v[54:57]
	ds_read_b128 v[226:229], v198 offset:34880
	s_waitcnt lgkmcnt(0)
	v_mfma_f32_16x16x32_bf16 v[54:57], v[222:225], v[226:229], v[54:57]
	ds_read_b128 v[226:229], v199 offset:34816
	s_waitcnt lgkmcnt(0)
	v_mfma_f32_16x16x32_bf16 v[50:53], v[218:221], v[226:229], v[50:53]
	ds_read_b128 v[226:229], v199 offset:34880
	s_waitcnt lgkmcnt(0)
	v_mfma_f32_16x16x32_bf16 v[50:53], v[222:225], v[226:229], v[50:53]
	ds_read_b128 v[226:229], v200 offset:34816
	s_waitcnt lgkmcnt(0)
	v_mfma_f32_16x16x32_bf16 v[70:73], v[218:221], v[226:229], v[70:73]
	ds_read_b128 v[226:229], v200 offset:34880
	s_waitcnt lgkmcnt(0)
	v_mfma_f32_16x16x32_bf16 v[70:73], v[222:225], v[226:229], v[70:73]
	ds_read_b128 v[226:229], v201 offset:34816
	s_waitcnt lgkmcnt(0)
	v_mfma_f32_16x16x32_bf16 v[62:65], v[218:221], v[226:229], v[62:65]
	ds_read_b128 v[218:221], v201 offset:34880
	s_waitcnt lgkmcnt(0)
	s_barrier
	ds_write2_b32 v0, v86, v90 offset1:16
	ds_write2_b32 v2, v88, v92 offset0:8 offset1:24
	ds_write2_b32 v0, v94, v87 offset0:32 offset1:132
	ds_write2_b32 v0, v91, v95 offset0:148 offset1:164
	ds_write2_b32 v2, v96, v89 offset0:40 offset1:140
	ds_write2_b32 v2, v93, v97 offset0:156 offset1:172
	v_add_u32_e32 v0, 0x8800, v203
	ds_write2_b32 v0, v98, v99 offset1:132
	v_add_u32_e32 v0, 0x8c00, v203
	ds_write2_b32 v0, v100, v101 offset0:8 offset1:140
	s_waitcnt lgkmcnt(0)
	s_barrier
	ds_read_b128 v[98:101], v207 offset:34816
	ds_read_b128 v[90:93], v207 offset:34832
	ds_read_b128 v[94:97], v207 offset:34848
	ds_read_b128 v[86:89], v207 offset:34864
	s_waitcnt lgkmcnt(12)
	v_mfma_f32_16x16x32_bf16 v[62:65], v[222:225], v[218:221], v[62:65]
	s_waitcnt lgkmcnt(3)
	v_mov_b32_e32 v220, v99
	s_waitcnt lgkmcnt(2)
	v_mov_b32_e32 v221, v91
	v_mov_b32_e32 v218, v98
	v_mov_b32_e32 v219, v90
	v_pk_mul_f32 v[220:221], v[220:221], v[220:221]
	s_waitcnt lgkmcnt(1)
	v_mov_b32_e32 v222, v95
	v_pk_fma_f32 v[218:219], v[218:219], v[218:219], v[220:221]
	v_mov_b32_e32 v220, v100
	v_mov_b32_e32 v221, v92
	v_pk_fma_f32 v[218:219], v[220:221], v[220:221], v[218:219]
	v_mov_b32_e32 v220, v101
	v_mov_b32_e32 v221, v93
	s_waitcnt lgkmcnt(0)
	v_mov_b32_e32 v223, v87
	v_pk_fma_f32 v[218:219], v[220:221], v[220:221], v[218:219]
	v_mov_b32_e32 v220, v94
	v_mov_b32_e32 v221, v86
	v_pk_mul_f32 v[222:223], v[222:223], v[222:223]
	v_xor_b32_e32 v2, 1, v177
	v_pk_fma_f32 v[220:221], v[220:221], v[220:221], v[222:223]
	v_mov_b32_e32 v222, v96
	v_mov_b32_e32 v223, v88
	v_pk_fma_f32 v[220:221], v[222:223], v[222:223], v[220:221]
	v_mov_b32_e32 v222, v97
	v_mov_b32_e32 v223, v89
	v_pk_fma_f32 v[220:221], v[222:223], v[222:223], v[220:221]
	v_add_f32_e32 v0, v218, v219
	v_cmp_lt_i32_e32 vcc, v2, v4
	v_add_f32_e32 v0, v0, v220
	v_add_f32_e32 v0, v0, v221
	v_cndmask_b32_e32 v2, v177, v2, vcc
	v_lshlrev_b32_e32 v2, 2, v2
	ds_bpermute_b32 v2, v2, v0
	s_waitcnt vmcnt(1)
	v_lshlrev_b32_e32 v218, 16, v82
	s_waitcnt lgkmcnt(0)
	v_add_f32_e32 v0, v0, v2
	v_xor_b32_e32 v2, 2, v177
	v_cmp_lt_i32_e32 vcc, v2, v4
	s_nop 1
	v_cndmask_b32_e32 v2, v177, v2, vcc
	v_lshlrev_b32_e32 v2, 2, v2
	ds_bpermute_b32 v2, v2, v0
	s_waitcnt lgkmcnt(0)
	v_add_f32_e32 v0, v0, v2
	v_xor_b32_e32 v2, 4, v177
	v_cmp_lt_i32_e32 vcc, v2, v4
	s_nop 1
	v_cndmask_b32_e32 v2, v177, v2, vcc
	v_lshlrev_b32_e32 v2, 2, v2
	ds_bpermute_b32 v2, v2, v0
	s_waitcnt lgkmcnt(0)
	v_add_f32_e32 v0, v0, v2
	v_fmamk_f32 v0, v0, 0x3c000000, v143
	v_cmp_gt_f32_e32 vcc, s90, v0
	v_mul_f32_e32 v2, 0x4b800000, v0
	s_nop 0
	v_cndmask_b32_e32 v0, v0, v2, vcc
	v_rsq_f32_e32 v0, v0
	s_nop 0
	v_mul_f32_e32 v2, 0x45800000, v0
	v_cndmask_b32_e32 v0, v0, v2, vcc
	v_mul_f32_e32 v2, 0xbfb8aa3b, v218
	v_exp_f32_e32 v2, v2
	v_mul_f32_e32 v219, v98, v0
	v_and_b32_e32 v98, 0xffff0000, v82
	v_mul_f32_e32 v99, v99, v0
	v_add_f32_e32 v2, 1.0, v2
	v_rcp_f32_e32 v102, v2
	v_mul_f32_e32 v2, 0xbfb8aa3b, v98
	v_exp_f32_e32 v2, v2
	v_mul_f32_e32 v95, v95, v0
	v_pk_mul_f32 v[218:219], v[102:103], v[218:219]
	v_mul_f32_e32 v91, v91, v0
	v_add_f32_e32 v2, 1.0, v2
	v_rcp_f32_e32 v2, v2
	v_mul_f32_e32 v4, v218, v219
	v_mul_f32_e32 v87, v87, v0
	v_pk_mul_f32 v[98:99], v[2:3], v[98:99]
	s_nop 0
	v_mul_f32_e32 v2, v98, v99
	v_mul_f32_e32 v99, v94, v0
	s_waitcnt vmcnt(0)
	v_lshlrev_b32_e32 v98, 16, v78
	v_and_b32_e32 v94, 0xffff0000, v78
	v_cvt_pk_bf16_f32 v82, v4, v2
	v_mul_f32_e32 v2, 0xbfb8aa3b, v98
	v_mul_f32_e32 v4, 0xbfb8aa3b, v94
	v_exp_f32_e32 v2, v2
	v_exp_f32_e32 v4, v4
	v_add_f32_e32 v2, 1.0, v2
	v_add_f32_e32 v4, 1.0, v4
	v_rcp_f32_e32 v110, v2
	v_rcp_f32_e32 v10, v4
	v_pk_mul_f32 v[98:99], v[110:111], v[98:99]
	v_pk_mul_f32 v[94:95], v[10:11], v[94:95]
	v_mul_f32_e32 v2, v98, v99
	v_mul_f32_e32 v4, v94, v95
	v_lshlrev_b32_e32 v94, 16, v83
	v_cvt_pk_bf16_f32 v78, v2, v4
	v_mul_f32_e32 v2, 0xbfb8aa3b, v94
	v_exp_f32_e32 v2, v2
	v_mul_f32_e32 v95, v100, v0
	v_add_f32_e32 v2, 1.0, v2
	v_rcp_f32_e32 v104, v2
	s_nop 0
	v_pk_mul_f32 v[94:95], v[104:105], v[94:95]
	s_nop 0
	v_mul_f32_e32 v2, v94, v95
	v_and_b32_e32 v94, 0xffff0000, v83
	v_mul_f32_e32 v4, 0xbfb8aa3b, v94
	v_exp_f32_e32 v4, v4
	v_mul_f32_e32 v95, v101, v0
	v_add_f32_e32 v4, 1.0, v4
	v_rcp_f32_e32 v4, v4
	s_nop 0
	v_pk_mul_f32 v[94:95], v[4:5], v[94:95]
	s_nop 0
	v_mul_f32_e32 v4, v94, v95
	v_lshlrev_b32_e32 v94, 16, v79
	v_cvt_pk_bf16_f32 v83, v2, v4
	v_mul_f32_e32 v2, 0xbfb8aa3b, v94
	v_exp_f32_e32 v2, v2
	v_mul_f32_e32 v95, v96, v0
	v_add_f32_e32 v2, 1.0, v2
	v_rcp_f32_e32 v112, v2
	s_nop 0
	v_pk_mul_f32 v[94:95], v[112:113], v[94:95]
	s_nop 0
	v_mul_f32_e32 v2, v94, v95
	v_and_b32_e32 v94, 0xffff0000, v79
	v_mul_f32_e32 v4, 0xbfb8aa3b, v94
	v_exp_f32_e32 v4, v4
	v_mul_f32_e32 v95, v97, v0
	v_add_f32_e32 v4, 1.0, v4
	v_rcp_f32_e32 v12, v4
	s_nop 0
	v_pk_mul_f32 v[94:95], v[12:13], v[94:95]
	s_nop 0
	v_mul_f32_e32 v4, v94, v95
	v_mul_f32_e32 v95, v90, v0
	v_lshlrev_b32_e32 v94, 16, v84
	v_and_b32_e32 v90, 0xffff0000, v84
	v_cvt_pk_bf16_f32 v79, v2, v4
	v_mul_f32_e32 v2, 0xbfb8aa3b, v94
	v_mul_f32_e32 v4, 0xbfb8aa3b, v90
	v_exp_f32_e32 v2, v2
	v_exp_f32_e32 v4, v4
	v_add_f32_e32 v2, 1.0, v2
	v_add_f32_e32 v4, 1.0, v4
	v_rcp_f32_e32 v106, v2
	v_rcp_f32_e32 v6, v4
	v_pk_mul_f32 v[94:95], v[106:107], v[94:95]
	v_pk_mul_f32 v[90:91], v[6:7], v[90:91]
	v_mul_f32_e32 v2, v94, v95
	v_mul_f32_e32 v4, v90, v91
	v_mul_f32_e32 v91, v86, v0
	v_lshlrev_b32_e32 v90, 16, v80
	v_and_b32_e32 v86, 0xffff0000, v80
	v_cvt_pk_bf16_f32 v84, v2, v4
	v_mul_f32_e32 v2, 0xbfb8aa3b, v90
	v_mul_f32_e32 v4, 0xbfb8aa3b, v86
	v_exp_f32_e32 v2, v2
	v_exp_f32_e32 v4, v4
	v_mov_b32_e32 v6, v211
	v_add_f32_e32 v2, 1.0, v2
	v_add_f32_e32 v4, 1.0, v4
	v_rcp_f32_e32 v114, v2
	v_rcp_f32_e32 v14, v4
	v_pk_mul_f32 v[90:91], v[114:115], v[90:91]
	v_pk_mul_f32 v[86:87], v[14:15], v[86:87]
	v_mul_f32_e32 v2, v90, v91
	v_mul_f32_e32 v4, v86, v87
	v_lshlrev_b32_e32 v86, 16, v85
	v_cvt_pk_bf16_f32 v80, v2, v4
	v_mul_f32_e32 v2, 0xbfb8aa3b, v86
	v_exp_f32_e32 v2, v2
	v_mul_f32_e32 v87, v92, v0
	v_add_f32_e32 v2, 1.0, v2
	v_rcp_f32_e32 v108, v2
	s_nop 0
	v_pk_mul_f32 v[86:87], v[108:109], v[86:87]
	s_nop 0
	v_mul_f32_e32 v2, v86, v87
	v_and_b32_e32 v86, 0xffff0000, v85
	v_mul_f32_e32 v4, 0xbfb8aa3b, v86
	v_exp_f32_e32 v4, v4
	v_mul_f32_e32 v87, v93, v0
	v_add_f32_e32 v4, 1.0, v4
	v_rcp_f32_e32 v8, v4
	s_nop 0
	v_pk_mul_f32 v[86:87], v[8:9], v[86:87]
	s_nop 0
	v_mul_f32_e32 v4, v86, v87
	v_lshlrev_b32_e32 v86, 16, v81
	v_cvt_pk_bf16_f32 v85, v2, v4
	v_mul_f32_e32 v2, 0xbfb8aa3b, v86
	v_exp_f32_e32 v2, v2
	v_mul_f32_e32 v87, v88, v0
	v_mov_b32_e32 v4, v210
	v_add_f32_e32 v2, 1.0, v2
	v_rcp_f32_e32 v116, v2
	s_nop 0
	v_pk_mul_f32 v[86:87], v[116:117], v[86:87]
	s_nop 0
	v_mul_f32_e32 v2, v86, v87
	v_and_b32_e32 v86, 0xffff0000, v81
	v_mul_f32_e32 v87, v89, v0
	v_mul_f32_e32 v0, 0xbfb8aa3b, v86
	v_exp_f32_e32 v0, v0
	s_nop 0
	v_add_f32_e32 v0, 1.0, v0
	v_rcp_f32_e32 v16, v0
	s_nop 0
	v_pk_mul_f32 v[86:87], v[16:17], v[86:87]
	s_nop 0
	v_mul_f32_e32 v0, v86, v87
	v_lshl_add_u64 v[86:87], s[50:51], 0, v[138:139]
	v_add_co_u32_e32 v86, vcc, s0, v86
	v_cvt_pk_bf16_f32 v81, v2, v0
	v_lshl_add_u64 v[138:139], v[138:139], 0, s[6:7]
	s_nop 0
	v_addc_co_u32_e32 v87, vcc, 0, v87, vcc
	global_store_dwordx4 v[86:87], v[82:85], off
	global_store_dwordx4 v[86:87], v[78:81], off offset:16
	v_mov_b32_e32 v0, v208
	v_mov_b32_e32 v2, v209
	v_mov_b32_e32 v16, v212
	v_mov_b32_e32 v78, v213
	v_mov_b32_e32 v79, v214
	v_mov_b32_e32 v80, v215
	s_cbranch_scc0 .LBB0_682
	.p2align	6

.LBB0_783:
	v_mov_b64_e32 v[2:3], s[48:49]
	s_ashr_i32 s13, s12, 31
	v_cmp_lt_i64_e32 vcc, s[14:15], v[2:3]
	s_lshl_b64 s[14:15], s[12:13], 19
	s_add_u32 s14, s94, s14
	s_addc_u32 s15, s95, s15
	s_and_b64 s[16:17], vcc, exec
	s_cselect_b32 s9, s15, s21
	s_cselect_b32 s13, s14, s20
	s_ashr_i32 s11, s10, 31
	s_lshl_b64 s[16:17], s[10:11], 19
	s_add_u32 s16, s26, s16
	s_addc_u32 s17, s27, s17
	s_and_b64 s[24:25], vcc, exec
	s_cselect_b32 s11, s17, s23
	s_cselect_b32 s62, s16, s22
	s_add_u32 s20, s20, 0x40080
	s_addc_u32 s21, s21, 0
	s_add_u32 s63, s22, 0x100
	v_mov_b32_e32 v2, 0
	s_addc_u32 s64, s23, 0
	s_mov_b32 s65, -2
	v_mov_b32_e32 v3, v2
	v_mov_b32_e32 v4, v2
	v_mov_b32_e32 v5, v2
	v_mov_b32_e32 v6, v2
	v_mov_b32_e32 v7, v2
	v_mov_b32_e32 v8, v2
	v_mov_b32_e32 v9, v2
	v_mov_b32_e32 v18, v2
	v_mov_b32_e32 v19, v2
	v_mov_b32_e32 v20, v2
	v_mov_b32_e32 v21, v2
	v_mov_b32_e32 v22, v2
	v_mov_b32_e32 v23, v2
	v_mov_b32_e32 v24, v2
	v_mov_b32_e32 v25, v2
	v_mov_b32_e32 v34, v2
	v_mov_b32_e32 v35, v2
	v_mov_b32_e32 v36, v2
	v_mov_b32_e32 v37, v2
	v_mov_b32_e32 v38, v2
	v_mov_b32_e32 v39, v2
	v_mov_b32_e32 v40, v2
	v_mov_b32_e32 v41, v2
	v_mov_b32_e32 v50, v2
	v_mov_b32_e32 v51, v2
	v_mov_b32_e32 v52, v2
	v_mov_b32_e32 v53, v2
	v_mov_b32_e32 v54, v2
	v_mov_b32_e32 v55, v2
	v_mov_b32_e32 v56, v2
	v_mov_b32_e32 v57, v2
	v_mov_b32_e32 v10, v2
	v_mov_b32_e32 v11, v2
	v_mov_b32_e32 v12, v2
	v_mov_b32_e32 v13, v2
	v_mov_b32_e32 v14, v2
	v_mov_b32_e32 v15, v2
	v_mov_b32_e32 v16, v2
	v_mov_b32_e32 v17, v2
	v_mov_b32_e32 v26, v2
	v_mov_b32_e32 v27, v2
	v_mov_b32_e32 v28, v2
	v_mov_b32_e32 v29, v2
	v_mov_b32_e32 v30, v2
	v_mov_b32_e32 v31, v2
	v_mov_b32_e32 v32, v2
	v_mov_b32_e32 v33, v2
	v_mov_b32_e32 v42, v2
	v_mov_b32_e32 v43, v2
	v_mov_b32_e32 v44, v2
	v_mov_b32_e32 v45, v2
	v_mov_b32_e32 v46, v2
	v_mov_b32_e32 v47, v2
	v_mov_b32_e32 v48, v2
	v_mov_b32_e32 v49, v2
	v_mov_b32_e32 v58, v2
	v_mov_b32_e32 v59, v2
	v_mov_b32_e32 v60, v2
	v_mov_b32_e32 v61, v2
	v_mov_b32_e32 v62, v2
	v_mov_b32_e32 v63, v2
	v_mov_b32_e32 v64, v2
	v_mov_b32_e32 v65, v2
	v_mov_b32_e32 v66, v2
	v_mov_b32_e32 v67, v2
	v_mov_b32_e32 v68, v2
	v_mov_b32_e32 v69, v2
	v_mov_b32_e32 v70, v2
	v_mov_b32_e32 v71, v2
	v_mov_b32_e32 v72, v2
	v_mov_b32_e32 v73, v2
	v_mov_b32_e32 v82, v2
	v_mov_b32_e32 v83, v2
	v_mov_b32_e32 v84, v2
	v_mov_b32_e32 v85, v2
	v_mov_b32_e32 v86, v2
	v_mov_b32_e32 v87, v2
	v_mov_b32_e32 v88, v2
	v_mov_b32_e32 v89, v2
	v_mov_b32_e32 v98, v2
	v_mov_b32_e32 v99, v2
	v_mov_b32_e32 v100, v2
	v_mov_b32_e32 v101, v2
	v_mov_b32_e32 v102, v2
	v_mov_b32_e32 v103, v2
	v_mov_b32_e32 v104, v2
	v_mov_b32_e32 v105, v2
	v_mov_b32_e32 v114, v2
	v_mov_b32_e32 v115, v2
	v_mov_b32_e32 v116, v2
	v_mov_b32_e32 v117, v2
	v_mov_b32_e32 v118, v2
	v_mov_b32_e32 v119, v2
	v_mov_b32_e32 v120, v2
	v_mov_b32_e32 v121, v2
	v_mov_b32_e32 v74, v2
	v_mov_b32_e32 v75, v2
	v_mov_b32_e32 v76, v2
	v_mov_b32_e32 v77, v2
	v_mov_b32_e32 v78, v2
	v_mov_b32_e32 v79, v2
	v_mov_b32_e32 v80, v2
	v_mov_b32_e32 v81, v2
	v_mov_b32_e32 v90, v2
	v_mov_b32_e32 v91, v2
	v_mov_b32_e32 v92, v2
	v_mov_b32_e32 v93, v2
	v_mov_b32_e32 v94, v2
	v_mov_b32_e32 v95, v2
	v_mov_b32_e32 v96, v2
	v_mov_b32_e32 v97, v2
	v_mov_b32_e32 v106, v2
	v_mov_b32_e32 v107, v2
	v_mov_b32_e32 v108, v2
	v_mov_b32_e32 v109, v2
	v_mov_b32_e32 v110, v2
	v_mov_b32_e32 v111, v2
	v_mov_b32_e32 v112, v2
	v_mov_b32_e32 v113, v2
	v_mov_b32_e32 v122, v2
	v_mov_b32_e32 v123, v2
	v_mov_b32_e32 v124, v2
	v_mov_b32_e32 v125, v2
	v_mov_b32_e32 v126, v2
	v_mov_b32_e32 v127, v2
	v_mov_b32_e32 v128, v2
	v_mov_b32_e32 v129, v2
	.p2align	6

.LBB0_810:
	s_ashr_i32 s3, s2, 31
	v_cmp_lt_i64_e32 vcc, s[8:9], v[150:151]
	s_lshl_b64 s[8:9], s[2:3], 17
	s_add_u32 s8, s33, s8
	s_addc_u32 s9, s34, s9
	s_and_b64 s[10:11], vcc, exec
	s_cselect_b32 s3, s9, s17
	s_cselect_b32 s65, s8, s16
	s_ashr_i32 s1, s0, 31
	s_lshl_b64 s[10:11], s[0:1], 17
	s_add_u32 s10, s35, s10
	s_addc_u32 s11, s36, s11
	s_and_b64 s[18:19], vcc, exec
	v_mov_b32_e32 v2, 0
	s_cselect_b32 s1, s11, s15
	s_cselect_b32 s70, s10, s14
	s_mov_b32 s22, 0
	s_mov_b64 s[18:19], -1
	s_mov_b64 s[20:21], 0
	v_mov_b32_e32 v3, v2
	v_mov_b32_e32 v4, v2
	v_mov_b32_e32 v5, v2
	v_mov_b32_e32 v6, v2
	v_mov_b32_e32 v7, v2
	v_mov_b32_e32 v8, v2
	v_mov_b32_e32 v9, v2
	v_mov_b32_e32 v10, v2
	v_mov_b32_e32 v11, v2
	v_mov_b32_e32 v12, v2
	v_mov_b32_e32 v13, v2
	v_mov_b32_e32 v18, v2
	v_mov_b32_e32 v19, v2
	v_mov_b32_e32 v20, v2
	v_mov_b32_e32 v21, v2
	v_mov_b32_e32 v26, v2
	v_mov_b32_e32 v27, v2
	v_mov_b32_e32 v28, v2
	v_mov_b32_e32 v29, v2
	v_mov_b32_e32 v34, v2
	v_mov_b32_e32 v35, v2
	v_mov_b32_e32 v36, v2
	v_mov_b32_e32 v37, v2
	v_mov_b32_e32 v42, v2
	v_mov_b32_e32 v43, v2
	v_mov_b32_e32 v44, v2
	v_mov_b32_e32 v45, v2
	v_mov_b32_e32 v50, v2
	v_mov_b32_e32 v51, v2
	v_mov_b32_e32 v52, v2
	v_mov_b32_e32 v53, v2
	v_mov_b32_e32 v14, v2
	v_mov_b32_e32 v15, v2
	v_mov_b32_e32 v16, v2
	v_mov_b32_e32 v17, v2
	v_mov_b32_e32 v22, v2
	v_mov_b32_e32 v23, v2
	v_mov_b32_e32 v24, v2
	v_mov_b32_e32 v25, v2
	v_mov_b32_e32 v30, v2
	v_mov_b32_e32 v31, v2
	v_mov_b32_e32 v32, v2
	v_mov_b32_e32 v33, v2
	v_mov_b32_e32 v38, v2
	v_mov_b32_e32 v39, v2
	v_mov_b32_e32 v40, v2
	v_mov_b32_e32 v41, v2
	v_mov_b32_e32 v46, v2
	v_mov_b32_e32 v47, v2
	v_mov_b32_e32 v48, v2
	v_mov_b32_e32 v49, v2
	v_mov_b32_e32 v54, v2
	v_mov_b32_e32 v55, v2
	v_mov_b32_e32 v56, v2
	v_mov_b32_e32 v57, v2
	v_mov_b32_e32 v58, v2
	v_mov_b32_e32 v59, v2
	v_mov_b32_e32 v60, v2
	v_mov_b32_e32 v61, v2
	v_mov_b32_e32 v62, v2
	v_mov_b32_e32 v63, v2
	v_mov_b32_e32 v64, v2
	v_mov_b32_e32 v65, v2
	v_mov_b32_e32 v66, v2
	v_mov_b32_e32 v67, v2
	v_mov_b32_e32 v68, v2
	v_mov_b32_e32 v69, v2
	v_mov_b32_e32 v70, v2
	v_mov_b32_e32 v71, v2
	v_mov_b32_e32 v72, v2
	v_mov_b32_e32 v73, v2
	v_mov_b32_e32 v74, v2
	v_mov_b32_e32 v75, v2
	v_mov_b32_e32 v76, v2
	v_mov_b32_e32 v77, v2
	v_mov_b32_e32 v82, v2
	v_mov_b32_e32 v83, v2
	v_mov_b32_e32 v84, v2
	v_mov_b32_e32 v85, v2
	v_mov_b32_e32 v90, v2
	v_mov_b32_e32 v91, v2
	v_mov_b32_e32 v92, v2
	v_mov_b32_e32 v93, v2
	v_mov_b32_e32 v98, v2
	v_mov_b32_e32 v99, v2
	v_mov_b32_e32 v100, v2
	v_mov_b32_e32 v101, v2
	v_mov_b32_e32 v106, v2
	v_mov_b32_e32 v107, v2
	v_mov_b32_e32 v108, v2
	v_mov_b32_e32 v109, v2
	v_mov_b32_e32 v114, v2
	v_mov_b32_e32 v115, v2
	v_mov_b32_e32 v116, v2
	v_mov_b32_e32 v117, v2
	v_mov_b32_e32 v78, v2
	v_mov_b32_e32 v79, v2
	v_mov_b32_e32 v80, v2
	v_mov_b32_e32 v81, v2
	v_mov_b32_e32 v86, v2
	v_mov_b32_e32 v87, v2
	v_mov_b32_e32 v88, v2
	v_mov_b32_e32 v89, v2
	v_mov_b32_e32 v94, v2
	v_mov_b32_e32 v95, v2
	v_mov_b32_e32 v96, v2
	v_mov_b32_e32 v97, v2
	v_mov_b32_e32 v102, v2
	v_mov_b32_e32 v103, v2
	v_mov_b32_e32 v104, v2
	v_mov_b32_e32 v105, v2
	v_mov_b32_e32 v110, v2
	v_mov_b32_e32 v111, v2
	v_mov_b32_e32 v112, v2
	v_mov_b32_e32 v113, v2
	v_mov_b32_e32 v118, v2
	v_mov_b32_e32 v119, v2
	v_mov_b32_e32 v120, v2
	v_mov_b32_e32 v121, v2
	v_mov_b32_e32 v122, v2
	v_mov_b32_e32 v123, v2
	v_mov_b32_e32 v124, v2
	v_mov_b32_e32 v125, v2
	v_mov_b32_e32 v126, v2
	v_mov_b32_e32 v127, v2
	v_mov_b32_e32 v128, v2
	v_mov_b32_e32 v129, v2
	.p2align	6
